# v43 without the s_nop between the attention K and V prefetch loads (address registers no longer overlap the destination)
# speedup vs baseline: 1.0089x; 1.0070x over previous
.LBB0_800:
	s_or_b64 exec, exec, s[6:7]
	v_readfirstlane_b32 s100, v166
	s_add_i32 s101, s87, 5
	s_cmp_lt_u32 s101, s100
	s_cselect_b32 s100, 0x20000, 0
	s_mov_b32 s101, 0
	v_lshl_add_u64 v[228:229], s[100:101], 0, v[228:229]
	s_lshr_b32 s100, s100, 10
	v_lshl_add_u64 v[230:231], s[100:101], 0, v[230:231]
	s_lshl_b32 s100, s100, 1
	v_lshl_add_u64 v[232:233], s[100:101], 0, v[232:233]
	s_waitcnt lgkmcnt(0)
	s_barrier
	global_load_dwordx4 v[36:39], v[228:229], off
	global_load_dwordx4 v[40:43], v[230:231], off
	s_add_i32 s0, s87, 3
	global_load_dword v131, v[232:233], off
	s_cmp_eq_u32 s87, 0
	s_cselect_b64 s[10:11], -1, 0
	v_cmp_ge_u32_e64 s[6:7], s0, v165
	v_cmp_lt_u32_e64 s[8:9], s0, v165
	s_or_b64 s[10:11], s[10:11], s[6:7]
	s_and_saveexec_b64 s[12:13], s[10:11]
	s_xor_b64 s[56:57], exec, s[12:13]
	s_cbranch_execz .LBB0_806
	s_and_saveexec_b64 s[10:11], s[6:7]
	v_add_u32_e32 v73, s84, v168
	v_add_u32_e32 v73, 0xfffff8c0, v73
	v_cmp_ge_i32_e64 s[6:7], s93, v73
	s_andn2_b64 s[8:9], s[8:9], exec
	s_and_b64 s[6:7], s[6:7], exec
	s_or_b64 s[8:9], s[8:9], s[6:7]
	s_or_b64 exec, exec, s[10:11]
	s_and_saveexec_b64 s[64:65], s[8:9]
	s_cbranch_execz .LBB0_805
	s_cmp_eq_u32 s87, 0
	s_cbranch_scc1 .Lattn_band1
	s_add_i32 s101, s87, 3
	v_readfirstlane_b32 s100, v165
	s_sub_i32 s100, s101, s100
	s_lshl_b32 s100, s100, 6
	s_add_i32 s100, s100, 63
	v_readfirstlane_b32 s101, v192
	s_lshr_b32 s101, s101, 6
	s_lshl_b32 s101, s101, 5
	s_cmp_le_i32 s100, s101
	s_cbranch_scc0 .Lattn_band1
	s_mov_b64 s[6:7], exec
	s_branch .Lattn_nb1

.LBB0_811:
	s_or_b64 exec, exec, s[6:7]
	v_readfirstlane_b32 s100, v166
	s_add_i32 s101, s87, 6
	s_cmp_lt_u32 s101, s100
	s_cselect_b32 s100, 0x20000, 0
	s_mov_b32 s101, 0
	v_lshl_add_u64 v[228:229], s[100:101], 0, v[228:229]
	s_lshr_b32 s100, s100, 10
	v_lshl_add_u64 v[230:231], s[100:101], 0, v[230:231]
	s_lshl_b32 s100, s100, 1
	v_lshl_add_u64 v[232:233], s[100:101], 0, v[232:233]
	s_waitcnt lgkmcnt(0)
	s_barrier
	global_load_dwordx4 v[44:47], v[228:229], off
	global_load_dwordx4 v[48:51], v[230:231], off
	s_add_i32 s6, s87, 4
	global_load_dword v167, v[232:233], off
	v_cmp_ge_u32_e64 s[6:7], s6, v165
	s_and_saveexec_b64 s[8:9], s[6:7]
	s_xor_b64 s[64:65], exec, s[8:9]
	s_cbranch_execz .LBB0_815
	v_add_u32_e32 v73, s84, v168
	v_add_u32_e32 v73, 0xfffff900, v73
	v_cmp_ge_i32_e64 s[6:7], s93, v73
	s_and_saveexec_b64 s[72:73], s[6:7]
	s_cbranch_execz .LBB0_814
	s_add_i32 s101, s87, 4
	v_readfirstlane_b32 s100, v165
	s_sub_i32 s100, s101, s100
	s_lshl_b32 s100, s100, 6
	s_add_i32 s100, s100, 63
	v_readfirstlane_b32 s101, v192
	s_lshr_b32 s101, s101, 6
	s_lshl_b32 s101, s101, 5
	s_cmp_le_i32 s100, s101
	s_cbranch_scc0 .Lattn_band2
	s_mov_b64 s[6:7], exec
	s_branch .Lattn_nb2

.LBB0_821:
	s_or_b64 exec, exec, s[6:7]
	v_readfirstlane_b32 s100, v166
	s_add_i32 s101, s87, 7
	s_cmp_lt_u32 s101, s100
	s_cselect_b32 s100, 0x20000, 0
	s_mov_b32 s101, 0
	v_lshl_add_u64 v[228:229], s[100:101], 0, v[228:229]
	s_lshr_b32 s100, s100, 10
	v_lshl_add_u64 v[230:231], s[100:101], 0, v[230:231]
	s_lshl_b32 s100, s100, 1
	v_lshl_add_u64 v[232:233], s[100:101], 0, v[232:233]
	s_waitcnt lgkmcnt(0)
	s_barrier
	global_load_dwordx4 v[52:55], v[228:229], off
	global_load_dwordx4 v[56:59], v[230:231], off
	v_cmp_ge_u32_e64 s[6:7], s8, v165
	global_load_dword v169, v[232:233], off
	s_and_saveexec_b64 s[8:9], s[6:7]
	s_xor_b64 s[64:65], exec, s[8:9]
	s_cbranch_execz .LBB0_825
	v_add_u32_e32 v73, s84, v168
	v_add_u32_e32 v73, 0xfffff940, v73
	v_cmp_ge_i32_e64 s[6:7], s93, v73
	s_and_saveexec_b64 s[72:73], s[6:7]
	s_cbranch_execz .LBB0_824
	s_add_i32 s101, s87, 5
	v_readfirstlane_b32 s100, v165
	s_sub_i32 s100, s101, s100
	s_lshl_b32 s100, s100, 6
	s_add_i32 s100, s100, 63
	v_readfirstlane_b32 s101, v192
	s_lshr_b32 s101, s101, 6
	s_lshl_b32 s101, s101, 5
	s_cmp_le_i32 s100, s101
	s_cbranch_scc0 .Lattn_band3
	s_mov_b64 s[6:7], exec
	s_branch .Lattn_nb3
